# odd-layer post-pass: next row's loads prefetched during the current row (copy into working registers at row top, counted vmcnt), per-phase-invariant gain vectors loaded once
# speedup vs baseline: 1.0012x; 1.0012x over previous
.LBB0_456:
	s_lshl_b32 s8, s22, 6
	s_add_i32 s8, s8, s14
	s_ashr_i32 s8, s8, 8
	s_lshl_b32 s9, s8, 1
	s_add_i32 s10, s9, s66
	s_ashr_i32 s9, s8, 31
	s_ashr_i32 s11, s10, 31
	s_lshl_b64 s[8:9], s[8:9], 17
	v_lshl_add_u64 v[60:61], v[34:35], 0, s[8:9]
	s_lshl_b64 s[8:9], s[10:11], 19
	s_lshl_b64 s[12:13], s[10:11], 18
	v_lshl_add_u64 v[66:67], v[48:49], 0, s[8:9]
	s_lshl_b64 s[8:9], s[10:11], 16
	v_lshl_add_u64 v[62:63], v[44:45], 0, s[12:13]
	v_lshl_add_u64 v[64:65], v[46:47], 0, s[12:13]
	v_lshl_add_u64 v[68:69], v[50:51], 0, s[8:9]
	v_add_u32_e32 v148, 0x1000, v4
	v_add_u32_e32 v149, 0x1000, v58
	global_load_dwordx4 v[104:107], v[28:29], off
	global_load_dwordx4 v[112:115], v[30:31], off
	global_load_dwordx4 v[124:127], v[36:37], off offset:16
	global_load_dwordx4 v[128:131], v[36:37], off
	global_load_dwordx4 v[136:139], v[40:41], off offset:16
	global_load_dwordx4 v[140:143], v[40:41], off
	s_mov_b32 s100, s19
	s_and_b32 s101, s100, 0x3ff
	s_and_b32 vcc_lo, s100, 0xff
	s_cmpk_gt_i32 s100, 0xfff
	s_cselect_b32 s101, s101, vcc_lo
	s_and_b32 vcc_lo, s101, 63
	s_lshr_b32 s101, s101, 6
	v_mov_b32_e32 v180, s101
	v_mov_b32_e32 v181, vcc_lo
	s_nop 0
	v_cndmask_b32_e64 v180, v180, v181, s[50:51]
	v_lshlrev_b32_e32 v180, 6, v180
	v_mov_b32_e32 v181, 0
	v_lshl_add_u64 v[182:183], v[26:27], 0, v[180:181]
	global_load_dwordx4 v[152:155], v[182:183], off
	v_lshl_add_u64 v[182:183], v[24:25], 0, v[180:181]
	s_nop 0
	global_load_dwordx4 v[156:159], v[182:183], off
	s_mul_hi_i32 s101, s100, 0x1600
	s_mul_i32 s100, s100, 0x1600
	s_add_u32 s100, s15, s100
	s_addc_u32 s101, s18, s101
	global_load_dwordx2 v[150:151], v56, s[100:101]
	global_load_dwordx2 v[160:161], v74, s[100:101] offset:512
	global_load_dwordx2 v[162:163], v74, s[100:101] offset:1024
	global_load_dwordx2 v[164:165], v74, s[100:101] offset:1536
	global_load_dwordx2 v[166:167], v56, s[100:101] offset:2048
	global_load_dwordx2 v[168:169], v56, s[100:101] offset:2560
	global_load_dwordx4 v[172:175], v4, s[100:101] offset:3072
	global_load_dwordx4 v[176:179], v148, s[100:101]
	global_load_dwordx2 v[170:171], v149, s[100:101] offset:1024
	s_mov_b32 s23, 0
	s_branch .LBB0_458

.LBB0_458:
	s_add_i32 s8, s19, s23
	s_cmpk_lt_i32 s8, 0x1000
	s_cselect_b64 s[16:17], -1, 0
	s_and_b32 s9, s8, 0x3ff
	s_and_b32 s21, s8, 0xff
	s_cmpk_gt_i32 s8, 0xfff
	s_cselect_b64 s[58:59], -1, 0
	s_and_b64 s[60:61], s[58:59], exec
	s_cselect_b32 s12, s9, s21
	s_ashr_i32 s9, s8, 31
	s_mul_i32 s10, s8, 0x1600
	s_mul_hi_i32 s11, s8, 0x1600
	s_add_u32 s10, s15, s10
	s_addc_u32 s11, s18, s11
	s_waitcnt lgkmcnt(0)
	s_lshl_b32 s20, s21, 8
	s_cmp_lg_u32 s23, 0
	s_cbranch_scc1 .Lpost_pf_w
	s_waitcnt vmcnt(0)
	s_branch .Lpost_pf_c
.Lpost_pf_w:
	s_waitcnt vmcnt(11)
.Lpost_pf_c:
	v_mov_b64_e32 v[20:21], v[150:151]
	v_mov_b64_e32 v[12:13], v[152:153]
	v_mov_b64_e32 v[14:15], v[154:155]
	v_mov_b64_e32 v[8:9], v[156:157]
	v_mov_b64_e32 v[10:11], v[158:159]
	v_mov_b64_e32 v[100:101], v[160:161]
	v_mov_b64_e32 v[102:103], v[162:163]
	v_mov_b64_e32 v[108:109], v[164:165]
	v_mov_b64_e32 v[110:111], v[166:167]
	v_mov_b64_e32 v[116:117], v[168:169]
	v_mov_b64_e32 v[144:145], v[170:171]
	v_mov_b64_e32 v[120:121], v[172:173]
	v_mov_b64_e32 v[122:123], v[174:175]
	v_mov_b64_e32 v[132:133], v[176:177]
	v_mov_b64_e32 v[134:135], v[178:179]
	s_add_i32 s100, s8, 1
	s_and_b32 s101, s100, 0x3ff
	s_and_b32 vcc_lo, s100, 0xff
	s_cmpk_gt_i32 s100, 0xfff
	s_cselect_b32 s101, s101, vcc_lo
	s_and_b32 vcc_lo, s101, 63
	s_lshr_b32 s101, s101, 6
	v_mov_b32_e32 v180, s101
	v_mov_b32_e32 v181, vcc_lo
	s_nop 0
	v_cndmask_b32_e64 v180, v180, v181, s[50:51]
	v_lshlrev_b32_e32 v180, 6, v180
	v_mov_b32_e32 v181, 0
	v_lshl_add_u64 v[182:183], v[26:27], 0, v[180:181]
	global_load_dwordx4 v[152:155], v[182:183], off
	v_lshl_add_u64 v[182:183], v[24:25], 0, v[180:181]
	s_nop 0
	global_load_dwordx4 v[156:159], v[182:183], off
	s_mul_hi_i32 s101, s100, 0x1600
	s_mul_i32 s100, s100, 0x1600
	s_add_u32 s100, s15, s100
	s_addc_u32 s101, s18, s101
	global_load_dwordx2 v[150:151], v56, s[100:101]
	global_load_dwordx2 v[160:161], v74, s[100:101] offset:512
	global_load_dwordx2 v[162:163], v74, s[100:101] offset:1024
	global_load_dwordx2 v[164:165], v74, s[100:101] offset:1536
	global_load_dwordx2 v[166:167], v56, s[100:101] offset:2048
	global_load_dwordx2 v[168:169], v56, s[100:101] offset:2560
	global_load_dwordx4 v[172:175], v4, s[100:101] offset:3072
	global_load_dwordx4 v[176:179], v148, s[100:101]
	global_load_dwordx2 v[170:171], v149, s[100:101] offset:1024
	v_lshlrev_b32_e32 v23, 16, v21
	v_lshlrev_b32_e32 v22, 16, v20
	v_and_b32_e32 v21, 0xffff0000, v21
	v_and_b32_e32 v20, 0xffff0000, v20
	v_pk_mul_f32 v[76:77], v[20:21], v[20:21]
	s_nop 0
	v_pk_fma_f32 v[76:77], v[22:23], v[22:23], v[76:77]
	s_nop 0
	v_add_f32_e32 v2, v76, v77
	v_mov_b32_e32 v77, v20
	v_mov_b32_e32 v76, v22
	s_nop 1
	v_add_f32_dpp v2, v2, v2 quad_perm:[1,0,3,2] row_mask:0xf bank_mask:0xf
	s_nop 1
	v_add_f32_dpp v2, v2, v2 quad_perm:[2,3,0,1] row_mask:0xf bank_mask:0xf
	s_nop 1
	v_add_f32_dpp v2, v2, v2 row_half_mirror row_mask:0xf bank_mask:0xf
	s_nop 1
	v_add_f32_dpp v2, v2, v2 row_mirror row_mask:0xf bank_mask:0xf
	v_fmamk_f32 v2, v2, 0x3c800000, v234
	v_mul_f32_e32 v5, 0x4f800000, v2
	v_cmp_gt_f32_e32 vcc, s3, v2
	s_nop 1
	v_cndmask_b32_e32 v2, v2, v5, vcc
	v_sqrt_f32_e32 v5, v2
	s_nop 0
	v_add_u32_e32 v20, -1, v5
	v_add_u32_e32 v22, 1, v5
	v_fma_f32 v57, -v20, v5, v2
	v_fma_f32 v59, -v22, v5, v2
	v_cmp_ge_f32_e64 s[62:63], 0, v57
	s_nop 1
	v_cndmask_b32_e64 v5, v5, v20, s[62:63]
	v_cmp_lt_f32_e64 s[62:63], 0, v59
	s_nop 1
	v_cndmask_b32_e64 v5, v5, v22, s[62:63]
	v_mul_f32_e32 v20, 0x37800000, v5
	v_cndmask_b32_e32 v5, v5, v20, vcc
	v_cmp_class_f32_e32 vcc, v2, v235
	v_mov_b32_e32 v20, v23
	s_nop 0
	v_cndmask_b32_e32 v2, v5, v2, vcc
	v_div_scale_f32 v5, s[12:13], v2, v2, 1.0
	v_rcp_f32_e32 v22, v5
	v_div_scale_f32 v23, vcc, 1.0, v2, 1.0
	s_lshl_b64 s[12:13], s[8:9], 11
	v_fma_f32 v57, -v5, v22, 1.0
	v_fmac_f32_e32 v22, v57, v22
	v_mul_f32_e32 v57, v23, v22
	v_fma_f32 v59, -v5, v57, v23
	v_fmac_f32_e32 v57, v59, v22
	v_fma_f32 v5, -v5, v57, v23
	v_div_fmas_f32 v5, v5, v22, v57
	v_div_fixup_f32 v2, v5, v2, 1.0
	v_pk_mul_f32 v[22:23], v[2:3], v[76:77] op_sel_hi:[0,1]
	v_pk_mul_f32 v[20:21], v[2:3], v[20:21] op_sel_hi:[0,1]
	v_pk_mul_f32 v[18:19], v[106:107], v[20:21]
	v_pk_mul_f32 v[20:21], v[104:105], v[22:23]
	ds_bpermute_b32 v22, v70, v20
	ds_bpermute_b32 v23, v70, v21
	ds_bpermute_b32 v76, v70, v18
	ds_bpermute_b32 v77, v70, v19
	v_lshl_add_u64 v[16:17], v[54:55], 0, s[12:13]
	s_waitcnt lgkmcnt(2)
	v_pk_mul_f32 v[22:23], v[12:13], v[22:23]
	s_nop 0
	v_xor_b32_e32 v57, 0x80000000, v22
	s_waitcnt lgkmcnt(0)
	v_pk_mul_f32 v[76:77], v[14:15], v[76:77]
	v_xor_b32_e32 v59, 0x80000000, v23
	v_xor_b32_e32 v2, 0x80000000, v76
	v_xor_b32_e32 v5, 0x80000000, v77
	v_cndmask_b32_e64 v23, v23, v59, s[52:53]
	v_cndmask_b32_e64 v22, v22, v57, s[52:53]
	v_cndmask_b32_e64 v77, v77, v5, s[52:53]
	v_cndmask_b32_e64 v76, v76, v2, s[52:53]
	v_pk_fma_f32 v[76:77], v[10:11], v[18:19], v[76:77]
	v_pk_fma_f32 v[22:23], v[8:9], v[20:21], v[22:23]
	v_cndmask_b32_e64 v19, v19, v77, s[58:59]
	v_cndmask_b32_e64 v21, v21, v23, s[58:59]
	v_cndmask_b32_e64 v20, v20, v22, s[58:59]
	v_cndmask_b32_e64 v18, v18, v76, s[58:59]
	v_pk_mul_f32 v[18:19], v[18:19], s[46:47] op_sel_hi:[1,0]
	v_pk_mul_f32 v[20:21], v[20:21], s[46:47] op_sel_hi:[1,0]
	s_nop 0
	v_cvt_pk_bf16_f32 v20, v20, v21
	v_cvt_pk_bf16_f32 v21, v18, v19
	global_store_dwordx2 v[16:17], v[20:21], off
	s_nop 0
	v_lshlrev_b32_e32 v77, 16, v101
	v_lshlrev_b32_e32 v76, 16, v100
	v_and_b32_e32 v23, 0xffff0000, v101
	v_and_b32_e32 v22, 0xffff0000, v100
	v_pk_mul_f32 v[78:79], v[22:23], v[22:23]
	s_nop 0
	v_pk_fma_f32 v[78:79], v[76:77], v[76:77], v[78:79]
	s_nop 0
	v_add_f32_e32 v2, v78, v79
	v_mov_b32_e32 v79, v22
	v_mov_b32_e32 v78, v76
	s_nop 1
	v_add_f32_dpp v2, v2, v2 quad_perm:[1,0,3,2] row_mask:0xf bank_mask:0xf
	s_nop 1
	v_add_f32_dpp v2, v2, v2 quad_perm:[2,3,0,1] row_mask:0xf bank_mask:0xf
	s_nop 1
	v_add_f32_dpp v2, v2, v2 row_half_mirror row_mask:0xf bank_mask:0xf
	s_nop 1
	v_add_f32_dpp v2, v2, v2 row_mirror row_mask:0xf bank_mask:0xf
	v_fmamk_f32 v2, v2, 0x3c800000, v234
	v_mul_f32_e32 v5, 0x4f800000, v2
	v_cmp_gt_f32_e32 vcc, s3, v2
	s_nop 1
	v_cndmask_b32_e32 v2, v2, v5, vcc
	v_sqrt_f32_e32 v5, v2
	s_nop 0
	v_add_u32_e32 v22, -1, v5
	v_add_u32_e32 v57, 1, v5
	v_fma_f32 v59, -v22, v5, v2
	v_fma_f32 v75, -v57, v5, v2
	v_cmp_ge_f32_e64 s[62:63], 0, v59
	s_nop 1
	v_cndmask_b32_e64 v5, v5, v22, s[62:63]
	v_cmp_lt_f32_e64 s[62:63], 0, v75
	s_nop 1
	v_cndmask_b32_e64 v5, v5, v57, s[62:63]
	v_mul_f32_e32 v22, 0x37800000, v5
	v_cndmask_b32_e32 v5, v5, v22, vcc
	v_cmp_class_f32_e32 vcc, v2, v235
	v_mov_b32_e32 v22, v77
	s_nop 0
	v_cndmask_b32_e32 v2, v5, v2, vcc
	v_div_scale_f32 v5, s[12:13], v2, v2, 1.0
	v_rcp_f32_e32 v57, v5
	v_div_scale_f32 v59, vcc, 1.0, v2, 1.0
	v_fma_f32 v75, -v5, v57, 1.0
	v_fmac_f32_e32 v57, v75, v57
	v_mul_f32_e32 v75, v59, v57
	v_fma_f32 v76, -v5, v75, v59
	v_fmac_f32_e32 v75, v76, v57
	v_fma_f32 v5, -v5, v75, v59
	v_div_fmas_f32 v5, v5, v57, v75
	v_div_fixup_f32 v2, v5, v2, 1.0
	v_pk_mul_f32 v[76:77], v[2:3], v[78:79] op_sel_hi:[0,1]
	v_pk_mul_f32 v[22:23], v[2:3], v[22:23] op_sel_hi:[0,1]
	v_pk_mul_f32 v[20:21], v[106:107], v[22:23]
	v_pk_mul_f32 v[18:19], v[104:105], v[76:77]
	ds_bpermute_b32 v22, v70, v18
	ds_bpermute_b32 v23, v70, v19
	ds_bpermute_b32 v76, v70, v20
	ds_bpermute_b32 v77, v70, v21
	s_waitcnt lgkmcnt(2)
	v_pk_mul_f32 v[22:23], v[12:13], v[22:23]
	s_nop 0
	v_xor_b32_e32 v57, 0x80000000, v22
	s_waitcnt lgkmcnt(0)
	v_pk_mul_f32 v[76:77], v[14:15], v[76:77]
	v_xor_b32_e32 v59, 0x80000000, v23
	v_xor_b32_e32 v2, 0x80000000, v76
	v_xor_b32_e32 v5, 0x80000000, v77
	v_cndmask_b32_e64 v23, v23, v59, s[52:53]
	v_cndmask_b32_e64 v22, v22, v57, s[52:53]
	v_cndmask_b32_e64 v77, v77, v5, s[52:53]
	v_cndmask_b32_e64 v76, v76, v2, s[52:53]
	v_pk_fma_f32 v[76:77], v[10:11], v[20:21], v[76:77]
	v_pk_fma_f32 v[22:23], v[8:9], v[18:19], v[22:23]
	v_cndmask_b32_e64 v21, v21, v77, s[58:59]
	v_cndmask_b32_e64 v19, v19, v23, s[58:59]
	v_cndmask_b32_e64 v18, v18, v22, s[58:59]
	v_cndmask_b32_e64 v20, v20, v76, s[58:59]
	v_pk_mul_f32 v[20:21], v[20:21], s[46:47] op_sel_hi:[1,0]
	v_pk_mul_f32 v[18:19], v[18:19], s[46:47] op_sel_hi:[1,0]
	s_nop 0
	v_cvt_pk_bf16_f32 v18, v18, v19
	v_cvt_pk_bf16_f32 v19, v20, v21
	global_store_dwordx2 v[16:17], v[18:19], off offset:512
	s_nop 0
	v_lshlrev_b32_e32 v77, 16, v103
	v_lshlrev_b32_e32 v76, 16, v102
	v_and_b32_e32 v23, 0xffff0000, v103
	v_and_b32_e32 v22, 0xffff0000, v102
	v_pk_mul_f32 v[78:79], v[22:23], v[22:23]
	s_nop 0
	v_pk_fma_f32 v[78:79], v[76:77], v[76:77], v[78:79]
	s_nop 0
	v_add_f32_e32 v2, v78, v79
	v_mov_b32_e32 v79, v22
	v_mov_b32_e32 v78, v76
	s_nop 1
	v_add_f32_dpp v2, v2, v2 quad_perm:[1,0,3,2] row_mask:0xf bank_mask:0xf
	s_nop 1
	v_add_f32_dpp v2, v2, v2 quad_perm:[2,3,0,1] row_mask:0xf bank_mask:0xf
	s_nop 1
	v_add_f32_dpp v2, v2, v2 row_half_mirror row_mask:0xf bank_mask:0xf
	s_nop 1
	v_add_f32_dpp v2, v2, v2 row_mirror row_mask:0xf bank_mask:0xf
	v_fmamk_f32 v2, v2, 0x3c800000, v234
	v_mul_f32_e32 v5, 0x4f800000, v2
	v_cmp_gt_f32_e32 vcc, s3, v2
	s_nop 1
	v_cndmask_b32_e32 v2, v2, v5, vcc
	v_sqrt_f32_e32 v5, v2
	s_nop 0
	v_add_u32_e32 v22, -1, v5
	v_add_u32_e32 v57, 1, v5
	v_fma_f32 v59, -v22, v5, v2
	v_fma_f32 v75, -v57, v5, v2
	v_cmp_ge_f32_e64 s[62:63], 0, v59
	s_nop 1
	v_cndmask_b32_e64 v5, v5, v22, s[62:63]
	v_cmp_lt_f32_e64 s[62:63], 0, v75
	s_nop 1
	v_cndmask_b32_e64 v5, v5, v57, s[62:63]
	v_mul_f32_e32 v22, 0x37800000, v5
	v_cndmask_b32_e32 v5, v5, v22, vcc
	v_cmp_class_f32_e32 vcc, v2, v235
	v_mov_b32_e32 v22, v77
	s_nop 0
	v_cndmask_b32_e32 v2, v5, v2, vcc
	v_div_scale_f32 v5, s[12:13], v2, v2, 1.0
	v_rcp_f32_e32 v57, v5
	v_div_scale_f32 v59, vcc, 1.0, v2, 1.0
	v_fma_f32 v75, -v5, v57, 1.0
	v_fmac_f32_e32 v57, v75, v57
	v_mul_f32_e32 v75, v59, v57
	v_fma_f32 v76, -v5, v75, v59
	v_fmac_f32_e32 v75, v76, v57
	v_fma_f32 v5, -v5, v75, v59
	v_div_fmas_f32 v5, v5, v57, v75
	v_div_fixup_f32 v2, v5, v2, 1.0
	v_pk_mul_f32 v[76:77], v[2:3], v[78:79] op_sel_hi:[0,1]
	v_pk_mul_f32 v[22:23], v[2:3], v[22:23] op_sel_hi:[0,1]
	v_pk_mul_f32 v[20:21], v[106:107], v[22:23]
	v_pk_mul_f32 v[18:19], v[104:105], v[76:77]
	ds_bpermute_b32 v22, v70, v18
	ds_bpermute_b32 v23, v70, v19
	ds_bpermute_b32 v76, v70, v20
	ds_bpermute_b32 v77, v70, v21
	s_waitcnt lgkmcnt(2)
	v_pk_mul_f32 v[22:23], v[12:13], v[22:23]
	s_nop 0
	v_xor_b32_e32 v57, 0x80000000, v22
	s_waitcnt lgkmcnt(0)
	v_pk_mul_f32 v[76:77], v[14:15], v[76:77]
	v_xor_b32_e32 v59, 0x80000000, v23
	v_xor_b32_e32 v2, 0x80000000, v76
	v_xor_b32_e32 v5, 0x80000000, v77
	v_cndmask_b32_e64 v23, v23, v59, s[52:53]
	v_cndmask_b32_e64 v22, v22, v57, s[52:53]
	v_cndmask_b32_e64 v77, v77, v5, s[52:53]
	v_cndmask_b32_e64 v76, v76, v2, s[52:53]
	v_pk_fma_f32 v[76:77], v[10:11], v[20:21], v[76:77]
	v_pk_fma_f32 v[22:23], v[8:9], v[18:19], v[22:23]
	v_cndmask_b32_e64 v21, v21, v77, s[58:59]
	v_cndmask_b32_e64 v19, v19, v23, s[58:59]
	v_cndmask_b32_e64 v18, v18, v22, s[58:59]
	v_cndmask_b32_e64 v20, v20, v76, s[58:59]
	v_pk_mul_f32 v[20:21], v[20:21], s[46:47] op_sel_hi:[1,0]
	v_pk_mul_f32 v[18:19], v[18:19], s[46:47] op_sel_hi:[1,0]
	s_nop 0
	v_cvt_pk_bf16_f32 v18, v18, v19
	v_cvt_pk_bf16_f32 v19, v20, v21
	global_store_dwordx2 v[16:17], v[18:19], off offset:1024
	s_nop 0
	v_lshlrev_b32_e32 v77, 16, v109
	v_lshlrev_b32_e32 v76, 16, v108
	v_and_b32_e32 v23, 0xffff0000, v109
	v_and_b32_e32 v22, 0xffff0000, v108
	v_pk_mul_f32 v[78:79], v[22:23], v[22:23]
	s_nop 0
	v_pk_fma_f32 v[78:79], v[76:77], v[76:77], v[78:79]
	s_nop 0
	v_add_f32_e32 v2, v78, v79
	v_mov_b32_e32 v79, v22
	v_mov_b32_e32 v78, v76
	s_nop 1
	v_add_f32_dpp v2, v2, v2 quad_perm:[1,0,3,2] row_mask:0xf bank_mask:0xf
	s_nop 1
	v_add_f32_dpp v2, v2, v2 quad_perm:[2,3,0,1] row_mask:0xf bank_mask:0xf
	s_nop 1
	v_add_f32_dpp v2, v2, v2 row_half_mirror row_mask:0xf bank_mask:0xf
	s_nop 1
	v_add_f32_dpp v2, v2, v2 row_mirror row_mask:0xf bank_mask:0xf
	v_fmamk_f32 v2, v2, 0x3c800000, v234
	v_mul_f32_e32 v5, 0x4f800000, v2
	v_cmp_gt_f32_e32 vcc, s3, v2
	s_nop 1
	v_cndmask_b32_e32 v2, v2, v5, vcc
	v_sqrt_f32_e32 v5, v2
	s_nop 0
	v_add_u32_e32 v22, -1, v5
	v_add_u32_e32 v57, 1, v5
	v_fma_f32 v59, -v22, v5, v2
	v_fma_f32 v75, -v57, v5, v2
	v_cmp_ge_f32_e64 s[62:63], 0, v59
	s_nop 1
	v_cndmask_b32_e64 v5, v5, v22, s[62:63]
	v_cmp_lt_f32_e64 s[62:63], 0, v75
	s_nop 1
	v_cndmask_b32_e64 v5, v5, v57, s[62:63]
	v_mul_f32_e32 v22, 0x37800000, v5
	v_cndmask_b32_e32 v5, v5, v22, vcc
	v_cmp_class_f32_e32 vcc, v2, v235
	v_mov_b32_e32 v22, v77
	s_nop 0
	v_cndmask_b32_e32 v2, v5, v2, vcc
	v_div_scale_f32 v5, s[12:13], v2, v2, 1.0
	v_rcp_f32_e32 v57, v5
	v_div_scale_f32 v59, vcc, 1.0, v2, 1.0
	v_fma_f32 v75, -v5, v57, 1.0
	v_fmac_f32_e32 v57, v75, v57
	v_mul_f32_e32 v75, v59, v57
	v_fma_f32 v76, -v5, v75, v59
	v_fmac_f32_e32 v75, v76, v57
	v_fma_f32 v5, -v5, v75, v59
	v_div_fmas_f32 v5, v5, v57, v75
	v_div_fixup_f32 v2, v5, v2, 1.0
	v_pk_mul_f32 v[76:77], v[2:3], v[78:79] op_sel_hi:[0,1]
	v_pk_mul_f32 v[22:23], v[2:3], v[22:23] op_sel_hi:[0,1]
	v_pk_mul_f32 v[20:21], v[106:107], v[22:23]
	v_pk_mul_f32 v[18:19], v[104:105], v[76:77]
	ds_bpermute_b32 v22, v70, v18
	ds_bpermute_b32 v23, v70, v19
	ds_bpermute_b32 v76, v70, v20
	ds_bpermute_b32 v77, v70, v21
	s_waitcnt lgkmcnt(2)
	v_pk_mul_f32 v[22:23], v[12:13], v[22:23]
	s_nop 0
	v_xor_b32_e32 v57, 0x80000000, v22
	s_waitcnt lgkmcnt(0)
	v_pk_mul_f32 v[76:77], v[14:15], v[76:77]
	v_xor_b32_e32 v59, 0x80000000, v23
	v_xor_b32_e32 v2, 0x80000000, v76
	v_xor_b32_e32 v5, 0x80000000, v77
	v_cndmask_b32_e64 v23, v23, v59, s[52:53]
	v_cndmask_b32_e64 v22, v22, v57, s[52:53]
	v_cndmask_b32_e64 v77, v77, v5, s[52:53]
	v_cndmask_b32_e64 v76, v76, v2, s[52:53]
	v_pk_fma_f32 v[76:77], v[10:11], v[20:21], v[76:77]
	v_pk_fma_f32 v[22:23], v[8:9], v[18:19], v[22:23]
	v_cndmask_b32_e64 v21, v21, v77, s[58:59]
	v_cndmask_b32_e64 v19, v19, v23, s[58:59]
	v_cndmask_b32_e64 v18, v18, v22, s[58:59]
	v_cndmask_b32_e64 v20, v20, v76, s[58:59]
	v_pk_mul_f32 v[20:21], v[20:21], s[46:47] op_sel_hi:[1,0]
	v_pk_mul_f32 v[18:19], v[18:19], s[46:47] op_sel_hi:[1,0]
	s_nop 0
	v_cvt_pk_bf16_f32 v18, v18, v19
	v_cvt_pk_bf16_f32 v19, v20, v21
	global_store_dwordx2 v[16:17], v[18:19], off offset:1536
	s_nop 0
	v_lshlrev_b32_e32 v23, 16, v111
	v_lshlrev_b32_e32 v22, 16, v110
	v_and_b32_e32 v21, 0xffff0000, v111
	v_and_b32_e32 v20, 0xffff0000, v110
	v_pk_mul_f32 v[76:77], v[20:21], v[20:21]
	s_nop 0
	v_pk_fma_f32 v[76:77], v[22:23], v[22:23], v[76:77]
	s_nop 0
	v_add_f32_e32 v2, v76, v77
	v_mov_b32_e32 v77, v20
	v_mov_b32_e32 v76, v22
	s_nop 1
	v_add_f32_dpp v2, v2, v2 quad_perm:[1,0,3,2] row_mask:0xf bank_mask:0xf
	s_nop 1
	v_add_f32_dpp v2, v2, v2 quad_perm:[2,3,0,1] row_mask:0xf bank_mask:0xf
	s_nop 1
	v_add_f32_dpp v2, v2, v2 row_half_mirror row_mask:0xf bank_mask:0xf
	s_nop 1
	v_add_f32_dpp v2, v2, v2 row_mirror row_mask:0xf bank_mask:0xf
	v_fmamk_f32 v2, v2, 0x3c800000, v234
	v_mul_f32_e32 v5, 0x4f800000, v2
	v_cmp_gt_f32_e32 vcc, s3, v2
	s_nop 1
	v_cndmask_b32_e32 v2, v2, v5, vcc
	v_sqrt_f32_e32 v5, v2
	s_nop 0
	v_add_u32_e32 v20, -1, v5
	v_add_u32_e32 v22, 1, v5
	v_fma_f32 v57, -v20, v5, v2
	v_fma_f32 v59, -v22, v5, v2
	v_cmp_ge_f32_e64 s[62:63], 0, v57
	s_nop 1
	v_cndmask_b32_e64 v5, v5, v20, s[62:63]
	v_cmp_lt_f32_e64 s[62:63], 0, v59
	s_nop 1
	v_cndmask_b32_e64 v5, v5, v22, s[62:63]
	v_mul_f32_e32 v20, 0x37800000, v5
	v_cndmask_b32_e32 v5, v5, v20, vcc
	v_cmp_class_f32_e32 vcc, v2, v235
	v_mov_b32_e32 v20, v23
	s_nop 0
	v_cndmask_b32_e32 v2, v5, v2, vcc
	v_div_scale_f32 v5, s[12:13], v2, v2, 1.0
	v_rcp_f32_e32 v22, v5
	v_div_scale_f32 v23, vcc, 1.0, v2, 1.0
	v_fma_f32 v57, -v5, v22, 1.0
	v_fmac_f32_e32 v22, v57, v22
	v_mul_f32_e32 v57, v23, v22
	v_fma_f32 v59, -v5, v57, v23
	v_fmac_f32_e32 v57, v59, v22
	v_fma_f32 v5, -v5, v57, v23
	v_div_fmas_f32 v5, v5, v22, v57
	v_div_fixup_f32 v2, v5, v2, 1.0
	v_pk_mul_f32 v[22:23], v[2:3], v[76:77] op_sel_hi:[0,1]
	v_pk_mul_f32 v[20:21], v[2:3], v[20:21] op_sel_hi:[0,1]
	v_pk_mul_f32 v[18:19], v[114:115], v[20:21]
	v_pk_mul_f32 v[16:17], v[112:113], v[22:23]
	s_mov_b64 vcc, s[60:61]
	s_cbranch_vccnz .LBB0_460
	s_lshl_b32 s90, s20, 2
	v_lshl_add_u64 v[20:21], v[62:63], 0, s[90:91]
	global_store_dwordx4 v[20:21], v[16:19], off
